# v082 + input RMSNorm phase: the two rows' cross-lane sum reductions issue their ds_bpermute pairs together (6 LDS round trips per iteration instead of 11); same add order
# speedup vs baseline: 1.0031x; 1.0031x over previous
; __device__ __forceinline__ unsigned pk2(float lo, float hi) { f32x2 v = {lo, hi}; bf16x2_t b = __builtin_convertvector(v, bf16x2_t); return __builtin_bit_cast(unsigned, b); }
; __device__ __forceinline__ void rms_row2_bf16(const gfloat* src0, const gfloat* src1, const gfloat* gain, gbf16* dst0, gbf16* dst1, int lane) {
;     const gf32x4* x0 = (const gf32x4*)src0 + lane; const gf32x4* x1 = (const gf32x4*)src1 + lane; const gf32x4* gr = (const gf32x4*)gain + lane;
;     f32x4 v[4], w[4], g[4]; float s = 0.f, t = 0.f;
; #pragma unroll
;     for (int j = 0; j < 4; ++j) { v[j] = x0[64 * j]; w[j] = x1[64 * j]; g[j] = gr[64 * j]; }
;     asm volatile("" ::: "memory");
; #pragma unroll
;     for (int j = 0; j < 4; ++j) { s += (v[j].x * v[j].x + v[j].y * v[j].y) + (v[j].z * v[j].z + v[j].w * v[j].w); t += (w[j].x * w[j].x + w[j].y * w[j].y) + (w[j].z * w[j].z + w[j].w * w[j].w); }
; #pragma unroll
;     for (int o = 1; o < 64; o <<= 1) { s += __shfl_xor(s, o); t += __shfl_xor(t, o); }
;     const float r0 = __builtin_amdgcn_rsqf(s * (1.0f / DM) + EPS), r1 = __builtin_amdgcn_rsqf(t * (1.0f / DM) + EPS);
;     gu32x2* o0 = (gu32x2*)dst0 + lane; gu32x2* o1 = (gu32x2*)dst1 + lane;
; #pragma unroll
;     for (int j = 0; j < 4; ++j) { u32x2 a, b;
;         a.x = pk2(v[j].x * r0 * g[j].x, v[j].y * r0 * g[j].y); a.y = pk2(v[j].z * r0 * g[j].z, v[j].w * r0 * g[j].w); o0[64 * j] = a;
;         b.x = pk2(w[j].x * r1 * g[j].x, w[j].y * r1 * g[j].y); b.y = pk2(w[j].z * r1 * g[j].z, w[j].w * r1 * g[j].w); o1[64 * j] = b; }
; }
; __global__ void __launch_bounds__(512, 2) mega_fwd(Args a) {
;     ...
;                 for (int m = gw; m < CH; m += 2 * NGW) { const int m1 = (m + NGW < CH) ? m + NGW : m; rms_row2_bf16(xin_ + (size_t)m * DM, xin_ + (size_t)m1 * DM, gain, xn + (size_t)m * DM, xn + (size_t)m1 * DM, lane); }
.LBB0_632:
	s_add_i32 s6, s10, s18
	s_cmp_lt_i32 s6, 0x8000
	s_cselect_b32 s4, s6, s10
	s_ashr_i32 s11, s10, 31
	s_ashr_i32 s5, s4, 31
	s_lshl_b64 s[8:9], s[10:11], 12
	v_lshl_add_u64 v[10:11], v[50:51], 0, s[8:9]
	s_lshl_b64 s[8:9], s[4:5], 12
	v_lshl_add_u64 v[12:13], v[50:51], 0, s[8:9]
	global_load_dwordx4 v[6:9], v[10:11], off
	global_load_dwordx4 v[2:5], v[12:13], off
	global_load_dwordx4 v[46:49], v[52:53], off
	global_load_dwordx4 v[38:41], v[10:11], off offset:1024
	global_load_dwordx4 v[18:21], v[12:13], off offset:1024
	global_load_dwordx4 v[42:45], v[52:53], off offset:1024
	global_load_dwordx4 v[30:33], v[10:11], off offset:2048
	global_load_dwordx4 v[14:17], v[12:13], off offset:2048
	global_load_dwordx4 v[34:37], v[52:53], off offset:2048
	global_load_dwordx4 v[22:25], v[10:11], off offset:3072
	s_nop 0
	global_load_dwordx4 v[10:13], v[12:13], off offset:3072
	s_nop 0
	global_load_dwordx4 v[26:29], v[52:53], off offset:3072
	s_lshl_b64 s[8:9], s[10:11], 11
	s_lshl_b64 s[4:5], s[4:5], 11
	s_add_i32 s10, s6, s18
	s_cmpk_gt_i32 s10, 0x7fff
	s_waitcnt vmcnt(0)
	v_pk_mul_f32 v[56:57], v[8:9], v[8:9]
	v_pk_mul_f32 v[58:59], v[6:7], v[6:7]
	s_waitcnt vmcnt(2)
	v_mul_f32_e32 v0, v22, v22
	v_pk_mov_b32 v[60:61], v[58:59], v[56:57] op_sel:[1,0]
	v_mov_b32_e32 v59, v57
	v_pk_add_f32 v[56:57], v[60:61], v[58:59]
	v_pk_mul_f32 v[58:59], v[4:5], v[4:5]
	v_pk_mul_f32 v[60:61], v[2:3], v[2:3]
	v_pk_add_f32 v[56:57], v[56:57], v[56:57] op_sel:[0,1] op_sel_hi:[1,0]
	v_pk_mov_b32 v[62:63], v[60:61], v[58:59] op_sel:[1,0]
	v_mov_b32_e32 v61, v59
	v_pk_add_f32 v[58:59], v[62:63], v[60:61]
	v_pk_mul_f32 v[60:61], v[40:41], v[40:41]
	v_pk_mul_f32 v[62:63], v[38:39], v[38:39]
	v_mov_b32_e32 v57, v0
	v_pk_mov_b32 v[64:65], v[62:63], v[60:61] op_sel:[1,0]
	v_mov_b32_e32 v63, v61
	v_pk_add_f32 v[60:61], v[64:65], v[62:63]
	v_pk_mul_f32 v[62:63], v[20:21], v[20:21]
	v_pk_mul_f32 v[64:65], v[18:19], v[18:19]
	v_pk_add_f32 v[60:61], v[60:61], v[60:61] op_sel:[0,1] op_sel_hi:[1,0]
	v_pk_mov_b32 v[66:67], v[64:65], v[62:63] op_sel:[1,0]
	v_mov_b32_e32 v65, v63
	v_pk_add_f32 v[62:63], v[66:67], v[64:65]
	v_mul_f32_e32 v64, v23, v23
	v_mov_b32_e32 v61, v64
	v_mul_f32_e32 v0, v31, v31
	v_mul_f32_e32 v65, v24, v24
	v_pk_add_f32 v[56:57], v[56:57], v[60:61]
	v_pk_fma_f32 v[60:61], v[30:31], v[30:31], v[0:1] op_sel_hi:[1,1,0]
	v_mul_f32_e32 v0, v33, v33
	v_mul_f32_e32 v66, v25, v25
	v_mov_b32_e32 v61, v65
	v_pk_fma_f32 v[64:65], v[32:33], v[32:33], v[0:1] op_sel_hi:[1,1,0]
	s_waitcnt vmcnt(1)
	v_mul_f32_e32 v0, v10, v10
	v_mov_b32_e32 v65, v66
	v_pk_add_f32 v[60:61], v[60:61], v[64:65]
	v_mul_f32_e32 v65, v13, v13
	v_pk_add_f32 v[56:57], v[56:57], v[60:61]
	v_mul_f32_e32 v60, v11, v11
	v_add_f32_e32 v64, v56, v57
	v_pk_add_f32 v[56:57], v[58:59], v[58:59] op_sel:[0,1] op_sel_hi:[1,0]
	v_pk_add_f32 v[58:59], v[62:63], v[62:63] op_sel:[0,1] op_sel_hi:[1,0]
	v_mov_b32_e32 v57, v0
	v_mov_b32_e32 v59, v60
	v_mul_f32_e32 v0, v15, v15
	v_mul_f32_e32 v61, v12, v12
	v_pk_add_f32 v[56:57], v[56:57], v[58:59]
	v_pk_fma_f32 v[58:59], v[14:15], v[14:15], v[0:1] op_sel_hi:[1,1,0]
	v_mul_f32_e32 v0, v17, v17
	v_mov_b32_e32 v59, v61
	v_pk_fma_f32 v[60:61], v[16:17], v[16:17], v[0:1] op_sel_hi:[1,1,0]
	s_nop 0
	v_mov_b32_e32 v61, v65
	v_pk_add_f32 v[58:59], v[58:59], v[60:61]
	v_lshl_add_u64 v[60:61], v[54:55], 0, s[4:5]
	v_pk_add_f32 v[56:57], v[56:57], v[58:59]
	v_lshl_add_u64 v[58:59], v[54:55], 0, s[8:9]
	v_add_f32_e32 v0, v56, v57
	ds_bpermute_b32 v56, v231, v64
	ds_bpermute_b32 v57, v231, v0
	s_waitcnt lgkmcnt(1)
	v_add_f32_e32 v56, v64, v56
	s_waitcnt lgkmcnt(0)
	v_add_f32_e32 v0, v0, v57
	ds_bpermute_b32 v57, v232, v56
	ds_bpermute_b32 v70, v232, v0
	s_waitcnt lgkmcnt(1)
	v_add_f32_e32 v56, v56, v57
	s_waitcnt lgkmcnt(0)
	v_add_f32_e32 v0, v0, v70
	ds_bpermute_b32 v57, v233, v56
	ds_bpermute_b32 v70, v233, v0
	s_waitcnt lgkmcnt(1)
	v_add_f32_e32 v56, v56, v57
	s_waitcnt lgkmcnt(0)
	v_add_f32_e32 v0, v0, v70
	ds_bpermute_b32 v57, v234, v56
	ds_bpermute_b32 v70, v234, v0
	s_waitcnt lgkmcnt(1)
	v_add_f32_e32 v56, v56, v57
	s_waitcnt lgkmcnt(0)
	v_add_f32_e32 v0, v0, v70
	ds_bpermute_b32 v57, v229, v56
	ds_bpermute_b32 v70, v229, v0
	s_waitcnt lgkmcnt(1)
	v_add_f32_e32 v56, v56, v57
	s_waitcnt lgkmcnt(0)
	v_add_f32_e32 v0, v0, v70
	ds_bpermute_b32 v71, v230, v56
	ds_bpermute_b32 v57, v230, v0
	s_waitcnt lgkmcnt(1)
	v_add_f32_e32 v56, v56, v71
	v_fmamk_f32 v56, v56, 0x3a800000, v235
	v_rsq_f32_e32 v56, v56
	s_waitcnt lgkmcnt(0)
	v_add_f32_e32 v0, v0, v57
	v_fmamk_f32 v0, v0, 0x3a800000, v235
	v_rsq_f32_e32 v0, v0
	v_pk_mul_f32 v[6:7], v[6:7], v[56:57] op_sel_hi:[1,0]
	v_pk_mul_f32 v[8:9], v[8:9], v[56:57] op_sel_hi:[1,0]
	v_pk_mul_f32 v[6:7], v[46:47], v[6:7]
	v_pk_mul_f32 v[2:3], v[2:3], v[0:1] op_sel_hi:[1,0]
	v_pk_mul_f32 v[4:5], v[4:5], v[0:1] op_sel_hi:[1,0]
	v_pk_mul_f32 v[8:9], v[48:49], v[8:9]
	v_pk_mul_f32 v[2:3], v[46:47], v[2:3]
	v_pk_mul_f32 v[4:5], v[48:49], v[4:5]
	v_cvt_pk_bf16_f32 v6, v6, v7
	v_cvt_pk_bf16_f32 v7, v8, v9
	v_cvt_pk_bf16_f32 v2, v2, v3
	v_cvt_pk_bf16_f32 v3, v4, v5
	global_store_dwordx2 v[58:59], v[6:7], off
	global_store_dwordx2 v[60:61], v[2:3], off
	v_pk_mul_f32 v[2:3], v[38:39], v[56:57] op_sel_hi:[1,0]
	v_pk_mul_f32 v[4:5], v[40:41], v[56:57] op_sel_hi:[1,0]
	v_pk_mul_f32 v[2:3], v[42:43], v[2:3]
	v_pk_mul_f32 v[4:5], v[44:45], v[4:5]
	v_cvt_pk_bf16_f32 v2, v2, v3
	v_cvt_pk_bf16_f32 v3, v4, v5
	global_store_dwordx2 v[58:59], v[2:3], off offset:512
	v_pk_mul_f32 v[2:3], v[18:19], v[0:1] op_sel_hi:[1,0]
	v_pk_mul_f32 v[4:5], v[20:21], v[0:1] op_sel_hi:[1,0]
	v_pk_mul_f32 v[2:3], v[42:43], v[2:3]
	v_pk_mul_f32 v[4:5], v[44:45], v[4:5]
	v_cvt_pk_bf16_f32 v2, v2, v3
	v_cvt_pk_bf16_f32 v3, v4, v5
	global_store_dwordx2 v[60:61], v[2:3], off offset:512
	v_pk_mul_f32 v[2:3], v[30:31], v[56:57] op_sel_hi:[1,0]
	v_pk_mul_f32 v[4:5], v[32:33], v[56:57] op_sel_hi:[1,0]
	v_pk_mul_f32 v[2:3], v[34:35], v[2:3]
	v_pk_mul_f32 v[4:5], v[36:37], v[4:5]
	v_cvt_pk_bf16_f32 v2, v2, v3
	v_cvt_pk_bf16_f32 v3, v4, v5
	global_store_dwordx2 v[58:59], v[2:3], off offset:1024
	v_pk_mul_f32 v[2:3], v[14:15], v[0:1] op_sel_hi:[1,0]
	v_pk_mul_f32 v[4:5], v[16:17], v[0:1] op_sel_hi:[1,0]
	v_pk_mul_f32 v[2:3], v[34:35], v[2:3]
	v_pk_mul_f32 v[4:5], v[36:37], v[4:5]
	v_cvt_pk_bf16_f32 v2, v2, v3
	v_cvt_pk_bf16_f32 v3, v4, v5
	global_store_dwordx2 v[60:61], v[2:3], off offset:1024
	v_pk_mul_f32 v[2:3], v[22:23], v[56:57] op_sel_hi:[1,0]
	v_pk_mul_f32 v[4:5], v[24:25], v[56:57] op_sel_hi:[1,0]
	s_waitcnt vmcnt(6)
	v_pk_mul_f32 v[2:3], v[26:27], v[2:3]
	v_pk_mul_f32 v[4:5], v[28:29], v[4:5]
	v_cvt_pk_bf16_f32 v2, v2, v3
	v_cvt_pk_bf16_f32 v3, v4, v5
	global_store_dwordx2 v[58:59], v[2:3], off offset:1536
	v_pk_mul_f32 v[2:3], v[10:11], v[0:1] op_sel_hi:[1,0]
	v_pk_mul_f32 v[4:5], v[12:13], v[0:1] op_sel_hi:[1,0]
	v_pk_mul_f32 v[2:3], v[26:27], v[2:3]
	v_pk_mul_f32 v[4:5], v[28:29], v[4:5]
	v_cvt_pk_bf16_f32 v2, v2, v3
	v_cvt_pk_bf16_f32 v3, v4, v5
	global_store_dwordx2 v[60:61], v[2:3], off offset:1536
	s_cbranch_scc0 .LBB0_632

; __device__ __forceinline__ void rms_row2_bf16(const gfloat* src0, const gfloat* src1, const gfloat* gain, gbf16* dst0, gbf16* dst1, int lane) {
;     const gf32x4* x0 = (const gf32x4*)src0 + lane; const gf32x4* x1 = (const gf32x4*)src1 + lane; const gf32x4* gr = (const gf32x4*)gain + lane;
;     f32x4 v[4], w[4], g[4]; float s = 0.f, t = 0.f;
; #pragma unroll
;     for (int j = 0; j < 4; ++j) { v[j] = x0[64 * j]; w[j] = x1[64 * j]; g[j] = gr[64 * j]; }
;     asm volatile("" ::: "memory");
; #pragma unroll
;     for (int j = 0; j < 4; ++j) { s += (v[j].x * v[j].x + v[j].y * v[j].y) + (v[j].z * v[j].z + v[j].w * v[j].w); t += (w[j].x * w[j].x + w[j].y * w[j].y) + (w[j].z * w[j].z + w[j].w * w[j].w); }
; #pragma unroll
;     for (int o = 1; o < 64; o <<= 1) { s += __shfl_xor(s, o); t += __shfl_xor(t, o); }
; __global__ void __launch_bounds__(512, 2) mega_fwd(Args a) {
;     ...
;                     for (int i0 = 0; i0 < CH / 8; i0 += 2 * G) { const size_t ra = (size_t)(m0 + i0) * DM, rb = (size_t)(m0 + i0 + G) * DM; rms_row2_bf16(xin_ + ra, xin_ + rb, gain, xn + ra, xn + rb, lane); }
.LBB0_635:
	s_add_i32 s0, s4, s6
	s_ashr_i32 s1, s0, 31
	s_add_i32 s2, s5, s6
	s_ashr_i32 s3, s2, 31
	s_lshl_b64 s[8:9], s[0:1], 12
	v_lshl_add_u64 v[44:45], v[2:3], 0, s[8:9]
	s_lshl_b64 s[8:9], s[2:3], 12
	v_lshl_add_u64 v[48:49], v[2:3], 0, s[8:9]
	global_load_dwordx4 v[8:11], v[44:45], off
	global_load_dwordx4 v[12:15], v[48:49], off
	global_load_dwordx4 v[16:19], v[4:5], off
	global_load_dwordx4 v[20:23], v[44:45], off offset:1024
	global_load_dwordx4 v[24:27], v[48:49], off offset:1024
	global_load_dwordx4 v[28:31], v[4:5], off offset:1024
	global_load_dwordx4 v[32:35], v[44:45], off offset:2048
	global_load_dwordx4 v[36:39], v[48:49], off offset:2048
	global_load_dwordx4 v[40:43], v[4:5], off offset:2048
	s_nop 0
	global_load_dwordx4 v[44:47], v[44:45], off offset:3072
	s_nop 0
	global_load_dwordx4 v[48:51], v[48:49], off offset:3072
	s_nop 0
	global_load_dwordx4 v[52:55], v[4:5], off offset:3072
	s_lshl_b64 s[0:1], s[0:1], 11
	s_add_i32 s6, s6, s50
	s_waitcnt vmcnt(0)
	v_pk_mul_f32 v[56:57], v[10:11], v[10:11]
	v_pk_mul_f32 v[58:59], v[8:9], v[8:9]
	s_waitcnt vmcnt(2)
	v_mul_f32_e32 v0, v44, v44
	v_pk_mov_b32 v[60:61], v[58:59], v[56:57] op_sel:[1,0]
	v_mov_b32_e32 v59, v57
	v_pk_add_f32 v[56:57], v[60:61], v[58:59]
	v_pk_mul_f32 v[58:59], v[14:15], v[14:15]
	v_pk_mul_f32 v[60:61], v[12:13], v[12:13]
	v_pk_add_f32 v[56:57], v[56:57], v[56:57] op_sel:[0,1] op_sel_hi:[1,0]
	v_pk_mov_b32 v[62:63], v[60:61], v[58:59] op_sel:[1,0]
	v_mov_b32_e32 v61, v59
	v_pk_add_f32 v[58:59], v[62:63], v[60:61]
	v_pk_mul_f32 v[60:61], v[22:23], v[22:23]
	v_pk_mul_f32 v[62:63], v[20:21], v[20:21]
	v_mov_b32_e32 v57, v0
	v_pk_mov_b32 v[64:65], v[62:63], v[60:61] op_sel:[1,0]
	v_mov_b32_e32 v63, v61
	v_pk_add_f32 v[60:61], v[64:65], v[62:63]
	v_pk_mul_f32 v[62:63], v[26:27], v[26:27]
	v_pk_mul_f32 v[64:65], v[24:25], v[24:25]
	v_pk_add_f32 v[60:61], v[60:61], v[60:61] op_sel:[0,1] op_sel_hi:[1,0]
	v_pk_mov_b32 v[66:67], v[64:65], v[62:63] op_sel:[1,0]
	v_mov_b32_e32 v65, v63
	v_pk_add_f32 v[62:63], v[66:67], v[64:65]
	v_mul_f32_e32 v64, v45, v45
	v_mov_b32_e32 v61, v64
	v_mul_f32_e32 v0, v33, v33
	v_mul_f32_e32 v65, v46, v46
	v_pk_add_f32 v[56:57], v[56:57], v[60:61]
	v_pk_fma_f32 v[60:61], v[32:33], v[32:33], v[0:1] op_sel_hi:[1,1,0]
	v_mul_f32_e32 v0, v35, v35
	v_mul_f32_e32 v66, v47, v47
	v_mov_b32_e32 v61, v65
	v_pk_fma_f32 v[64:65], v[34:35], v[34:35], v[0:1] op_sel_hi:[1,1,0]
	s_waitcnt vmcnt(1)
	v_mul_f32_e32 v0, v48, v48
	v_mov_b32_e32 v65, v66
	v_pk_add_f32 v[60:61], v[60:61], v[64:65]
	v_mul_f32_e32 v65, v51, v51
	v_pk_add_f32 v[56:57], v[56:57], v[60:61]
	v_mul_f32_e32 v60, v49, v49
	v_add_f32_e32 v64, v56, v57
	v_pk_add_f32 v[56:57], v[58:59], v[58:59] op_sel:[0,1] op_sel_hi:[1,0]
	v_pk_add_f32 v[58:59], v[62:63], v[62:63] op_sel:[0,1] op_sel_hi:[1,0]
	v_mov_b32_e32 v57, v0
	v_mov_b32_e32 v59, v60
	v_mul_f32_e32 v0, v37, v37
	v_mul_f32_e32 v61, v50, v50
	v_pk_add_f32 v[56:57], v[56:57], v[58:59]
	v_pk_fma_f32 v[58:59], v[36:37], v[36:37], v[0:1] op_sel_hi:[1,1,0]
	v_mul_f32_e32 v0, v39, v39
	v_mov_b32_e32 v59, v61
	v_pk_fma_f32 v[60:61], v[38:39], v[38:39], v[0:1] op_sel_hi:[1,1,0]
	s_nop 0
	v_mov_b32_e32 v61, v65
	v_pk_add_f32 v[58:59], v[58:59], v[60:61]
	s_nop 0
	v_pk_add_f32 v[56:57], v[56:57], v[58:59]
	v_lshl_add_u64 v[58:59], v[6:7], 0, s[0:1]
	v_add_f32_e32 v0, v56, v57
	ds_bpermute_b32 v56, v231, v64
	ds_bpermute_b32 v57, v231, v0
	s_lshl_b64 s[0:1], s[2:3], 11
	v_lshl_add_u64 v[60:61], v[6:7], 0, s[0:1]
	s_cmpk_gt_i32 s6, 0xfff
	s_waitcnt lgkmcnt(1)
; __device__ __forceinline__ unsigned pk2(float lo, float hi) { f32x2 v = {lo, hi}; bf16x2_t b = __builtin_convertvector(v, bf16x2_t); return __builtin_bit_cast(unsigned, b); }
; __device__ __forceinline__ void rms_row2_bf16(const gfloat* src0, const gfloat* src1, const gfloat* gain, gbf16* dst0, gbf16* dst1, int lane) {
;     ...
;     for (int o = 1; o < 64; o <<= 1) { s += __shfl_xor(s, o); t += __shfl_xor(t, o); }
;     const float r0 = __builtin_amdgcn_rsqf(s * (1.0f / DM) + EPS), r1 = __builtin_amdgcn_rsqf(t * (1.0f / DM) + EPS);
;     gu32x2* o0 = (gu32x2*)dst0 + lane; gu32x2* o1 = (gu32x2*)dst1 + lane;
; #pragma unroll
;     for (int j = 0; j < 4; ++j) { u32x2 a, b;
;         a.x = pk2(v[j].x * r0 * g[j].x, v[j].y * r0 * g[j].y); a.y = pk2(v[j].z * r0 * g[j].z, v[j].w * r0 * g[j].w); o0[64 * j] = a;
;         b.x = pk2(w[j].x * r1 * g[j].x, w[j].y * r1 * g[j].y); b.y = pk2(w[j].z * r1 * g[j].z, w[j].w * r1 * g[j].w); o1[64 * j] = b; }
	v_add_f32_e32 v56, v64, v56
	s_waitcnt lgkmcnt(0)
	v_add_f32_e32 v0, v0, v57
	ds_bpermute_b32 v57, v232, v56
	ds_bpermute_b32 v70, v232, v0
	s_waitcnt lgkmcnt(1)
	v_add_f32_e32 v56, v56, v57
	s_waitcnt lgkmcnt(0)
	v_add_f32_e32 v0, v0, v70
	ds_bpermute_b32 v57, v233, v56
	ds_bpermute_b32 v70, v233, v0
	s_waitcnt lgkmcnt(1)
	v_add_f32_e32 v56, v56, v57
	s_waitcnt lgkmcnt(0)
	v_add_f32_e32 v0, v0, v70
	ds_bpermute_b32 v57, v234, v56
	ds_bpermute_b32 v70, v234, v0
	s_waitcnt lgkmcnt(1)
	v_add_f32_e32 v56, v56, v57
	s_waitcnt lgkmcnt(0)
	v_add_f32_e32 v0, v0, v70
	ds_bpermute_b32 v57, v229, v56
	ds_bpermute_b32 v70, v229, v0
	s_waitcnt lgkmcnt(1)
	v_add_f32_e32 v56, v56, v57
	s_waitcnt lgkmcnt(0)
	v_add_f32_e32 v0, v0, v70
	ds_bpermute_b32 v71, v230, v56
	ds_bpermute_b32 v57, v230, v0
	s_waitcnt lgkmcnt(1)
	v_add_f32_e32 v56, v56, v71
	s_waitcnt lgkmcnt(0)
	v_add_f32_e32 v57, v0, v57
	v_fmamk_f32 v0, v56, 0x3a800000, v235
	v_rsq_f32_e32 v0, v0
	v_fmamk_f32 v56, v57, 0x3a800000, v235
	v_rsq_f32_e32 v56, v56
	v_pk_mul_f32 v[8:9], v[8:9], v[0:1] op_sel_hi:[1,0]
	v_pk_mul_f32 v[10:11], v[10:11], v[0:1] op_sel_hi:[1,0]
	v_pk_mul_f32 v[8:9], v[16:17], v[8:9]
	v_pk_mul_f32 v[10:11], v[18:19], v[10:11]
	v_cvt_pk_bf16_f32 v8, v8, v9
	v_cvt_pk_bf16_f32 v9, v10, v11
	global_store_dwordx2 v[58:59], v[8:9], off
	v_pk_mul_f32 v[8:9], v[12:13], v[56:57] op_sel_hi:[1,0]
	v_pk_mul_f32 v[10:11], v[14:15], v[56:57] op_sel_hi:[1,0]
	v_pk_mul_f32 v[8:9], v[16:17], v[8:9]
	v_pk_mul_f32 v[10:11], v[18:19], v[10:11]
	v_cvt_pk_bf16_f32 v8, v8, v9
	v_cvt_pk_bf16_f32 v9, v10, v11
	global_store_dwordx2 v[60:61], v[8:9], off
	v_pk_mul_f32 v[8:9], v[20:21], v[0:1] op_sel_hi:[1,0]
	v_pk_mul_f32 v[10:11], v[22:23], v[0:1] op_sel_hi:[1,0]
	v_pk_mul_f32 v[8:9], v[28:29], v[8:9]
	v_pk_mul_f32 v[10:11], v[30:31], v[10:11]
	v_cvt_pk_bf16_f32 v8, v8, v9
	v_cvt_pk_bf16_f32 v9, v10, v11
	global_store_dwordx2 v[58:59], v[8:9], off offset:512
	v_pk_mul_f32 v[8:9], v[24:25], v[56:57] op_sel_hi:[1,0]
	v_pk_mul_f32 v[10:11], v[26:27], v[56:57] op_sel_hi:[1,0]
	v_pk_mul_f32 v[8:9], v[28:29], v[8:9]
	v_pk_mul_f32 v[10:11], v[30:31], v[10:11]
	v_cvt_pk_bf16_f32 v8, v8, v9
	v_cvt_pk_bf16_f32 v9, v10, v11
	global_store_dwordx2 v[60:61], v[8:9], off offset:512
	v_pk_mul_f32 v[8:9], v[32:33], v[0:1] op_sel_hi:[1,0]
	v_pk_mul_f32 v[10:11], v[34:35], v[0:1] op_sel_hi:[1,0]
	v_pk_mul_f32 v[8:9], v[40:41], v[8:9]
	v_pk_mul_f32 v[10:11], v[42:43], v[10:11]
	v_cvt_pk_bf16_f32 v8, v8, v9
	v_cvt_pk_bf16_f32 v9, v10, v11
	global_store_dwordx2 v[58:59], v[8:9], off offset:1024
	v_pk_mul_f32 v[8:9], v[36:37], v[56:57] op_sel_hi:[1,0]
	v_pk_mul_f32 v[10:11], v[38:39], v[56:57] op_sel_hi:[1,0]
	v_pk_mul_f32 v[8:9], v[40:41], v[8:9]
	v_pk_mul_f32 v[10:11], v[42:43], v[10:11]
	v_cvt_pk_bf16_f32 v8, v8, v9
	v_cvt_pk_bf16_f32 v9, v10, v11
	global_store_dwordx2 v[60:61], v[8:9], off offset:1024
	v_pk_mul_f32 v[8:9], v[44:45], v[0:1] op_sel_hi:[1,0]
	v_pk_mul_f32 v[10:11], v[46:47], v[0:1] op_sel_hi:[1,0]
	s_waitcnt vmcnt(6)
	v_pk_mul_f32 v[8:9], v[52:53], v[8:9]
	v_pk_mul_f32 v[10:11], v[54:55], v[10:11]
	v_cvt_pk_bf16_f32 v8, v8, v9
	v_cvt_pk_bf16_f32 v9, v10, v11
	global_store_dwordx2 v[58:59], v[8:9], off offset:1536
	v_pk_mul_f32 v[8:9], v[48:49], v[56:57] op_sel_hi:[1,0]
	v_pk_mul_f32 v[10:11], v[50:51], v[56:57] op_sel_hi:[1,0]
	v_pk_mul_f32 v[8:9], v[52:53], v[8:9]
	v_pk_mul_f32 v[10:11], v[54:55], v[10:11]
	v_cvt_pk_bf16_f32 v8, v8, v9
	v_cvt_pk_bf16_f32 v9, v10, v11
	global_store_dwordx2 v[60:61], v[8:9], off offset:1536
	s_cbranch_scc0 .LBB0_635
